# S5 sequence split moved from 32/32 to 48/16 super-tiles (state-only tiles are cheaper than full tiles, so the second CU of a pair takes the shorter output range)
# baseline (speedup 1.0000x reference)
.LBB0_827:
	s_and_b64 vcc, exec, s[0:1]
	s_cbranch_vccz .LBB0_923
	v_readlane_b32 s0, v251, 17
	s_cmpk_gt_i32 s0, 0xff
	s_cbranch_scc1 .LBB0_923
	s_lshr_b32 s101, s0, 7
	s_mul_i32 s100, s101, 16
	s_add_i32 s100, s100, 48
	s_mul_i32 s101, s101, 48
	v_readlane_b32 s0, v251, 22
	s_add_u32 s50, s0, 0x38400000
	s_movk_i32 s0, 0x400
	v_readlane_b32 s1, v251, 23
	v_cmp_gt_i32_e64 s[6:7], s0, v172
	v_readlane_b32 s0, v251, 13
	s_addc_u32 s51, s1, 0
	s_waitcnt lgkmcnt(0)
	v_lshrrev_b32_e32 v1, 4, v170
	s_andn2_b32 s0, s0, 63
	s_waitcnt vmcnt(0)
	v_bfe_u32 v110, v172, 4, 4
	v_lshlrev_b32_e32 v12, 2, v1
	s_add_i32 s0, s0, 64
	v_max_i32_e32 v39, 0x200, v172
	v_and_b32_e32 v108, 15, v172
	v_ashrrev_i32_e32 v4, 6, v172
	v_lshlrev_b32_e32 v8, 3, v110
	v_or_b32_e32 v22, s0, v12
	v_or_b32_e32 v23, 1, v12
	v_or_b32_e32 v24, 2, v12
	v_or_b32_e32 v26, 16, v12
	v_or_b32_e32 v28, 18, v12
	v_or_b32_e32 v30, 32, v12
	v_or_b32_e32 v32, 34, v12
	v_or_b32_e32 v34, 48, v12
	v_or_b32_e32 v12, 50, v12
	v_sub_u32_e32 v39, v39, v172
	v_lshlrev_b32_e32 v109, 3, v172
	v_and_b32_e32 v5, -4, v4
	v_add_u32_e32 v0, 0, v8
	v_mul_u32_u24_e32 v9, 56, v110
	v_lshlrev_b32_e32 v10, 2, v108
	v_lshlrev_b32_e32 v25, 3, v24
	v_or_b32_e32 v24, s0, v24
	v_lshlrev_b32_e32 v27, 3, v26
	v_or_b32_e32 v26, s0, v26
	v_lshlrev_b32_e32 v29, 3, v28
	v_or_b32_e32 v28, s0, v28
	v_lshlrev_b32_e32 v31, 3, v30
	v_or_b32_e32 v30, s0, v30
	v_lshlrev_b32_e32 v33, 3, v32
	v_or_b32_e32 v32, s0, v32
	v_lshlrev_b32_e32 v35, 3, v34
	v_or_b32_e32 v34, s0, v34
	v_lshlrev_b32_e32 v36, 3, v12
	v_or_b32_e32 v12, s0, v12
	v_add_u32_e32 v39, 0x1ff, v39
	s_add_i32 s0, 0, 0x10a04
	v_cmp_eq_u32_e32 vcc, 0, v5
	v_cmp_eq_u32_e64 s[8:9], v110, v108
	v_add3_u32 v111, v0, v9, v10
	v_lshrrev_b32_e32 v0, 1, v170
	v_add_u32_e32 v40, s0, v109
	s_movk_i32 s0, 0x19ff
	v_lshlrev_b32_e32 v42, 3, v39
	s_and_b64 s[56:57], vcc, s[8:9]
	v_and_b32_e32 v11, 8, v0
	v_readlane_b32 s2, v251, 26
	v_and_b32_e32 v0, 1, v172
	v_cmp_lt_u32_e32 vcc, s0, v39
	v_and_b32_e32 v42, 0xfffff000, v42
	s_brev_b32 s0, 4
	s_lshl_b32 s1, s2, 4
	v_cmp_eq_u32_e64 s[8:9], 0, v0
	v_mov_b32_e32 v0, 0x3ffffffe
	v_lshrrev_b32_e32 v41, 9, v39
	v_cmp_gt_u32_e64 s[20:21], s0, v39
	v_add_u32_e32 v39, v40, v42
	v_or_b32_e32 v13, s1, v108
	v_bitop3_b32 v0, s1, v0, v108 bitop3:0xc8
	s_movk_i32 s1, 0x440
	v_cmp_ge_u32_e64 s[22:23], v39, v40
	v_cmp_gt_i32_e64 s[10:11], s1, v172
	s_and_b64 s[0:1], s[22:23], s[20:21]
	v_or_b32_e32 v4, 3, v4
	s_and_b64 s[22:23], vcc, s[0:1]
	s_add_i32 s0, 0, 0x2000
	v_lshl_add_u32 v128, v4, 9, s0
	v_lshl_add_u32 v129, v5, 9, s0
	s_add_i32 s0, 0, 0x4000
	v_lshrrev_b32_e32 v9, 5, v170
	v_add_u32_e32 v131, s0, v8
	s_add_i32 s0, 0, 0xe800
	v_cmp_ge_i32_e64 s[12:13], s2, v9
	v_sub_u32_e32 v18, s2, v9
	v_or_b32_e32 v20, 2, v9
	v_or_b32_e32 v21, 4, v9
	v_or_b32_e32 v9, 6, v9
	v_lshl_add_u32 v132, v172, 2, s0
	v_readlane_b32 s0, v251, 24
	v_add_u32_e32 v10, 0, v10
	v_ashrrev_i32_e32 v14, 1, v13
	v_and_b32_e32 v17, 48, v172
	v_lshl_add_u32 v117, v13, 1, 0
	v_mul_u32_u24_e32 v13, 0x10c, v108
	v_cmp_ge_i32_e64 s[14:15], s2, v20
	v_sub_u32_e32 v20, s2, v20
	v_cmp_ge_i32_e64 s[16:17], s2, v21
	v_sub_u32_e32 v21, s2, v21
	v_cmp_ge_i32_e64 s[18:19], s2, v9
	v_sub_u32_e32 v9, s2, v9
	v_lshlrev_b32_e32 v96, 1, v108
	v_readlane_b32 s1, v251, 25
	s_load_dwordx2 s[52:53], s[48:49], 0x68
	s_load_dwordx2 s[54:55], s[48:49], 0x28
	s_load_dwordx8 s[24:31], s[48:49], 0x48
	v_lshlrev_b32_e32 v15, 1, v170
	v_add3_u32 v118, v10, v13, v17
	v_lshl_add_u32 v18, v18, 10, v10
	v_lshl_add_u32 v20, v20, 10, v10
	v_lshl_add_u32 v21, v21, 10, v10
	v_lshl_add_u32 v9, v9, 10, v10
	v_lshlrev_b32_e32 v10, 5, v1
	v_mul_u32_u24_e32 v124, 0x440, v1
	v_lshl_add_u64 v[98:99], s[0:1], 0, v[96:97]
	s_add_i32 s0, s2, 0x1800
	v_lshlrev_b32_e32 v1, 13, v1
	v_and_b32_e32 v15, 64, v15
	v_add_u32_e32 v134, s0, v1
	v_readlane_b32 s0, v251, 15
	v_ashrrev_i32_e32 v2, 5, v172
	v_lshl_add_u32 v37, v14, 7, 0
	v_sub_u32_e32 v14, v14, v15
	v_ashrrev_i32_e32 v15, 8, v172
	v_add_u32_e32 v173, 0x200, v172
	s_lshl_b32 s48, s0, 4
	s_add_i32 s0, s2, 0x1000
	v_and_b32_e32 v92, -2, v2
	v_lshlrev_b32_e32 v6, 9, v108
	s_add_i32 s33, 0, 0x10a00
	v_or_b32_e32 v94, 1, v2
	v_lshlrev_b32_e32 v119, 10, v5
	v_lshlrev_b32_e32 v120, 3, v15
	v_mul_i32_i24_e32 v121, 0x1100, v15
	v_ashrrev_i32_e32 v15, 8, v173
	v_add_u32_e32 v41, 1, v41
	v_add_u32_e32 v135, s0, v1
	s_add_i32 s0, s2, 0x800
	v_lshl_add_u32 v3, v170, 7, 0
	v_add_u32_e32 v7, s33, v6
	v_lshl_add_u32 v112, v0, 2, 0
	v_bfe_u32 v113, v172, 1, 3
	v_and_b32_e32 v0, 8, v109
	v_mul_u32_u24_e32 v16, 0x110, v108
	v_lshlrev_b32_e32 v13, 3, v92
	v_lshlrev_b32_e32 v2, 3, v94
	v_lshlrev_b32_e32 v19, 6, v11
	v_lshlrev_b32_e32 v22, 3, v22
	v_lshlrev_b32_e32 v24, 3, v24
	v_lshlrev_b32_e32 v26, 3, v26
	v_lshlrev_b32_e32 v28, 3, v28
	v_lshlrev_b32_e32 v30, 3, v30
	v_lshlrev_b32_e32 v32, 3, v32
	v_lshlrev_b32_e32 v34, 3, v34
	v_lshlrev_b32_e32 v12, 3, v12
	v_lshlrev_b32_e32 v11, 3, v11
	v_lshlrev_b32_e32 v14, 3, v14
	v_lshlrev_b32_e32 v122, 3, v15
	v_mul_i32_i24_e32 v123, 0x1100, v15
	v_mul_u32_u24_e32 v125, 0x110, v23
	v_or_b32_e32 v15, 0x400, v119
	v_or_b32_e32 v23, 0x800, v119
	v_lshlrev_b32_e32 v38, 10, v4
	v_and_b32_e32 v126, 0xfffffe, v41
	v_readlane_b32 s49, v251, 17
	s_and_b32 s49, s49, 0x7f
	v_add_u32_e32 v136, s0, v1
	s_add_i32 s0, 0, 0x6000
	v_cmp_lt_u32_e64 s[4:5], 63, v172
	v_mul_u32_u24_e32 v114, 0x110, v110
	v_lshlrev_b32_e32 v115, 5, v113
	v_lshlrev_b32_e32 v116, 1, v0
	v_ashrrev_i32_e32 v93, 31, v92
	v_ashrrev_i32_e32 v95, 31, v94
	v_lshl_add_u32 v127, v126, 9, v172
	v_cmp_ne_u32_e64 s[20:21], v41, v126
	v_add_u32_e32 v130, 0, v6
	v_add_u32_e32 v133, 0xfffffe00, v172
	s_lshl_b32 s35, s49, 4
	v_add_u32_e32 v137, s2, v1
	v_add3_u32 v138, v16, v17, s0
	v_add_u32_e32 v139, v3, v13
	v_add_u32_e32 v140, v3, v2
	v_add_u32_e32 v141, v111, v15
	v_add_u32_e32 v142, v111, v23
	v_add_u32_e32 v143, v111, v38
	v_add_u32_e32 v144, v7, v10
	v_add_u32_e32 v145, 0, v22
	v_add_u32_e32 v146, v7, v25
	v_add_u32_e32 v147, 0, v24
	v_add_u32_e32 v148, v7, v27
	v_add_u32_e32 v149, 0, v26
	v_add_u32_e32 v150, v7, v29
	v_add_u32_e32 v151, 0, v28
	v_add_u32_e32 v152, v7, v31
	v_add_u32_e32 v153, 0, v30
	v_add_u32_e32 v154, v7, v33
	v_add_u32_e32 v155, 0, v32
	v_add_u32_e32 v156, v7, v35
	v_add_u32_e32 v157, 0, v34
	v_add_u32_e32 v158, v7, v36
	v_add_u32_e32 v159, 0, v12
	v_add_u32_e32 v160, v37, v11
	v_add_u32_e32 v161, 0, v14
	v_lshlrev_b32_e32 v96, 1, v0
	v_add_u32_e32 v162, v18, v19
	v_add_u32_e32 v163, v20, v19
	v_add_u32_e32 v164, v21, v19
	v_add_u32_e32 v165, v9, v19
	s_branch .LBB0_831
